# diff-attention loop: hoist V/K fragment ds_reads into free VGPRs; ds_bpermute max-reduce -> v_permlane16/32_swap
# speedup vs baseline: 1.0901x; 1.0149x over previous
.LBB0_305:
	ds_read_b128 v[204:207], v128 offset:19456
	ds_read_b128 v[208:211], v128 offset:19520
	ds_read_b128 v[216:219], v128 offset:21760
	ds_read_b128 v[220:223], v128 offset:21824
	ds_read_b128 v[224:227], v128 offset:24064
	ds_read_b128 v[228:231], v128 offset:24128
	ds_read_b128 v[232:235], v128 offset:26368
	ds_read_b128 v[236:239], v128 offset:26432
	v_exp_f32_e32 v103, v88
	v_exp_f32_e32 v102, v80
	v_exp_f32_e32 v89, v89
	v_exp_f32_e32 v88, v81
	v_exp_f32_e32 v131, v90
	v_exp_f32_e32 v130, v82
	v_exp_f32_e32 v91, v91
	v_exp_f32_e32 v90, v83
	v_exp_f32_e32 v133, v84
	v_exp_f32_e32 v151, v96
	v_exp_f32_e32 v132, v76
	v_exp_f32_e32 v150, v72
	v_exp_f32_e32 v96, v73
	v_pk_add_f32 v[72:73], v[102:103], 0 op_sel_hi:[1,0]
	v_exp_f32_e32 v135, v85
	v_exp_f32_e32 v134, v77
	v_pk_add_f32 v[72:73], v[88:89], v[72:73]
	v_exp_f32_e32 v147, v86
	v_exp_f32_e32 v146, v78
	v_pk_add_f32 v[72:73], v[130:131], v[72:73]
	v_exp_f32_e32 v149, v87
	v_exp_f32_e32 v148, v79
	v_pk_add_f32 v[72:73], v[90:91], v[72:73]
	v_exp_f32_e32 v97, v97
	v_pk_add_f32 v[72:73], v[132:133], v[72:73]
	v_exp_f32_e32 v153, v98
	v_pk_add_f32 v[72:73], v[134:135], v[72:73]
	v_exp_f32_e32 v152, v74
	v_pk_add_f32 v[72:73], v[146:147], v[72:73]
	v_exp_f32_e32 v99, v99
	v_pk_add_f32 v[72:73], v[148:149], v[72:73]
	v_exp_f32_e32 v98, v75
	v_exp_f32_e32 v155, v92
	v_pk_add_f32 v[72:73], v[150:151], v[72:73]
	v_exp_f32_e32 v154, v64
	v_exp_f32_e32 v93, v93
	v_pk_add_f32 v[72:73], v[96:97], v[72:73]
	v_exp_f32_e32 v92, v65
	v_exp_f32_e32 v157, v94
	v_exp_f32_e32 v156, v66
	v_pk_add_f32 v[64:65], v[152:153], v[72:73]
	v_exp_f32_e32 v95, v95
	v_exp_f32_e32 v94, v67
	v_pk_add_f32 v[64:65], v[98:99], v[64:65]
	v_cvt_pk_bf16_f32 v68, v103, v89
	v_pk_add_f32 v[64:65], v[154:155], v[64:65]
	v_cvt_pk_bf16_f32 v69, v131, v91
	v_pk_add_f32 v[64:65], v[92:93], v[64:65]
	v_cvt_pk_bf16_f32 v70, v133, v135
	v_pk_add_f32 v[64:65], v[156:157], v[64:65]
	v_cvt_pk_bf16_f32 v71, v147, v149
	v_pk_add_f32 v[64:65], v[94:95], v[64:65]
	v_cvt_pk_bf16_f32 v84, v151, v97
	v_pk_add_f32 v[118:119], v[64:65], v[100:101]
	v_cvt_pk_bf16_f32 v85, v153, v99
	v_cvt_pk_bf16_f32 v86, v155, v93
	v_cvt_pk_bf16_f32 v87, v157, v95
	v_cvt_pk_bf16_f32 v64, v102, v88
	v_cvt_pk_bf16_f32 v65, v130, v90
	v_cvt_pk_bf16_f32 v66, v132, v134
	v_cvt_pk_bf16_f32 v67, v146, v148
	v_cvt_pk_bf16_f32 v72, v150, v96
	v_cvt_pk_bf16_f32 v73, v152, v98
	v_cvt_pk_bf16_f32 v74, v154, v92
	v_cvt_pk_bf16_f32 v75, v156, v94
	s_setprio 1
	s_waitcnt lgkmcnt(0)
	v_mfma_f32_16x16x32_bf16 v[44:47], v[204:207], v[68:71], v[44:47]
	v_mfma_f32_16x16x32_bf16 v[76:79], v[204:207], v[64:67], v[60:63]
	v_mfma_f32_16x16x32_bf16 v[60:63], v[208:211], v[84:87], v[44:47]
	v_mfma_f32_16x16x32_bf16 v[44:47], v[208:211], v[72:75], v[76:79]
	v_mfma_f32_16x16x32_bf16 v[56:59], v[216:219], v[68:71], v[56:59]
	v_mfma_f32_16x16x32_bf16 v[40:43], v[216:219], v[64:67], v[40:43]
	v_mfma_f32_16x16x32_bf16 v[56:59], v[220:223], v[84:87], v[56:59]
	v_mfma_f32_16x16x32_bf16 v[40:43], v[220:223], v[72:75], v[40:43]
	v_mfma_f32_16x16x32_bf16 v[52:55], v[224:227], v[68:71], v[52:55]
	v_mfma_f32_16x16x32_bf16 v[36:39], v[224:227], v[64:67], v[36:39]
	v_mfma_f32_16x16x32_bf16 v[52:55], v[228:231], v[84:87], v[52:55]
	v_mfma_f32_16x16x32_bf16 v[36:39], v[228:231], v[72:75], v[36:39]
	v_mfma_f32_16x16x32_bf16 v[32:35], v[232:235], v[64:67], v[32:35]
	v_mfma_f32_16x16x32_bf16 v[48:51], v[232:235], v[68:71], v[48:51]
	v_mfma_f32_16x16x32_bf16 v[48:51], v[236:239], v[84:87], v[48:51]
	v_mfma_f32_16x16x32_bf16 v[32:35], v[236:239], v[72:75], v[32:35]
	s_setprio 0
	s_add_i32 s4, s4, 2
	s_cmp_lt_u32 s0, s7
	s_waitcnt vmcnt(5)
	ds_write_b128 v122, v[24:27]
	s_waitcnt vmcnt(4)
	ds_write_b64 v123, v[28:29] offset:5120
	ds_write_b64 v124, v[30:31] offset:5120
	s_waitcnt vmcnt(3)
	ds_write_b64 v125, v[20:21] offset:5120
	ds_write_b64 v126, v[22:23] offset:5120
	s_waitcnt lgkmcnt(0)
	s_barrier
	s_cbranch_scc0 .LBB0_324
.LBB0_306:
	s_add_i32 s0, s4, -1
	s_min_i32 s2, s0, s1
	v_lshl_add_u32 v20, s2, 6, v108
	v_ashrrev_i32_e32 v21, 31, v20
	v_lshlrev_b64 v[20:21], 9, v[20:21]
	v_lshl_add_u64 v[20:21], v[114:115], 0, v[20:21]
	s_lshl_b32 s94, s2, 7
	global_load_dwordx4 v[24:27], v[20:21], off
	v_lshl_add_u64 v[20:21], v[110:111], 0, s[94:95]
	v_lshl_add_u64 v[22:23], v[112:113], 0, s[94:95]
	global_load_dwordx4 v[28:31], v[20:21], off
	s_nop 0
	global_load_dwordx4 v[20:23], v[22:23], off
	s_setprio 1
	ds_read_b128 v[72:75], v127
	ds_read_b128 v[76:79], v127 offset:1280
	ds_read_b128 v[248:251], v127 offset:2560
	ds_read_b128 v[130:133], v127 offset:3840
	v_xor_b32_e32 v64, 0x80000000, v117
	v_pk_add_f32 v[68:69], v[116:117], 0 neg_lo:[1,1] neg_hi:[1,1]
	v_mov_b32_e32 v65, v64
	v_mov_b32_e32 v66, v64
	v_mov_b32_e32 v67, v64
	v_mov_b32_e32 v69, v68
	v_mov_b32_e32 v70, v68
	v_mov_b32_e32 v71, v68
	s_waitcnt vmcnt(7) lgkmcnt(3)
	v_mfma_f32_16x16x32_bf16 v[88:91], v[72:75], v[0:3], v[64:67]
	s_waitcnt vmcnt(6)
	v_mfma_f32_16x16x32_bf16 v[84:87], v[72:75], v[4:7], v[68:71]
	s_waitcnt lgkmcnt(2)
	v_mfma_f32_16x16x32_bf16 v[92:95], v[76:79], v[0:3], v[64:67]
	v_mfma_f32_16x16x32_bf16 v[72:75], v[76:79], v[4:7], v[68:71]
	s_waitcnt lgkmcnt(1)
	v_mfma_f32_16x16x32_bf16 v[100:103], v[248:251], v[0:3], v[64:67]
	v_mfma_f32_16x16x32_bf16 v[80:83], v[248:251], v[4:7], v[68:71]
	s_waitcnt lgkmcnt(0)
	v_mfma_f32_16x16x32_bf16 v[96:99], v[130:133], v[0:3], v[64:67]
	v_mfma_f32_16x16x32_bf16 v[76:79], v[130:133], v[4:7], v[68:71]
	s_setprio 0
	s_nop 0
	v_max_f32_e32 v65, v89, v89
	v_max_f32_e32 v66, v88, v88
	v_max_f32_e32 v65, v66, v65
	v_max_f32_e32 v66, v91, v91
	v_max_f32_e32 v67, v90, v90
	v_max_f32_e32 v66, v67, v66
	v_max_f32_e32 v67, v95, v95
	v_max_f32_e32 v69, v94, v94
	v_max_f32_e32 v67, v69, v67
	v_max3_f32 v67, v92, v93, v67
	v_max3_f32 v65, v65, v66, v67
	v_max_f32_e32 v66, v103, v103
	v_max_f32_e32 v67, v102, v102
	v_max_f32_e32 v66, v67, v66
	v_max_f32_e32 v67, v99, v99
	v_max_f32_e32 v69, v98, v98
	v_max_f32_e32 v67, v69, v67
	v_max3_f32 v66, v100, v101, v66
	v_max3_f32 v67, v96, v97, v67
	v_max3_f32 v65, v65, v66, v67
	v_mov_b32_e32 v66, v65
	v_max_f32_e32 v67, v84, v84
	v_max_f32_e32 v69, v86, v86
	v_max_f32_e32 v70, v74, v74
	s_mov_b32 s2, 0x41000000
	s_nop 1
	v_permlane16_swap_b32_e32 v66, v65
	v_max_f32_e32 v65, v65, v66
	v_mov_b32_e32 v66, v65
	s_nop 1
	v_permlane32_swap_b32_e32 v66, v65
	v_max_f32_e32 v65, v65, v66
	v_max_f32_e32 v66, v85, v85
	v_max_f32_e32 v66, v67, v66
	v_max_f32_e32 v67, v87, v87
	v_max_f32_e32 v67, v69, v67
	v_max_f32_e32 v69, v75, v75
	v_max_f32_e32 v69, v70, v69
	v_max3_f32 v69, v72, v73, v69
	v_max3_f32 v66, v66, v67, v69
	v_max_f32_e32 v67, v83, v83
	v_max_f32_e32 v69, v82, v82
	v_max_f32_e32 v67, v69, v67
	v_max_f32_e32 v69, v79, v79
	v_max_f32_e32 v70, v78, v78
	v_max_f32_e32 v69, v70, v69
	v_max3_f32 v67, v80, v81, v67
	v_max3_f32 v69, v76, v77, v69
	v_max3_f32 v66, v66, v67, v69
	v_mov_b32_e32 v67, v66
	s_nop 1
	v_permlane16_swap_b32_e32 v67, v66
	v_max_f32_e32 v66, v66, v67
	v_mov_b32_e32 v67, v66
	s_nop 1
	v_permlane32_swap_b32_e32 v67, v66
	v_max_f32_e32 v66, v66, v67
	v_max_f32_e32 v67, v65, v66
	v_cmp_lt_f32_e32 vcc, s2, v67
	s_cbranch_vccz .LBB0_308
	v_max_f32_e32 v64, v65, v65
	v_max_f32_e32 v64, 0, v64
	v_pk_add_f32 v[88:89], v[88:89], v[64:65] op_sel_hi:[1,0] neg_lo:[0,1] neg_hi:[0,1]
	v_pk_add_f32 v[90:91], v[90:91], v[64:65] op_sel_hi:[1,0] neg_lo:[0,1] neg_hi:[0,1]
	v_pk_add_f32 v[92:93], v[92:93], v[64:65] op_sel_hi:[1,0] neg_lo:[0,1] neg_hi:[0,1]
	v_pk_add_f32 v[94:95], v[94:95], v[64:65] op_sel_hi:[1,0] neg_lo:[0,1] neg_hi:[0,1]
	v_pk_add_f32 v[100:101], v[100:101], v[64:65] op_sel_hi:[1,0] neg_lo:[0,1] neg_hi:[0,1]
	v_pk_add_f32 v[102:103], v[102:103], v[64:65] op_sel_hi:[1,0] neg_lo:[0,1] neg_hi:[0,1]
	v_pk_add_f32 v[96:97], v[96:97], v[64:65] op_sel_hi:[1,0] neg_lo:[0,1] neg_hi:[0,1]
	v_pk_add_f32 v[98:99], v[98:99], v[64:65] op_sel_hi:[1,0] neg_lo:[0,1] neg_hi:[0,1]
	v_max_f32_e32 v65, v66, v66
	v_exp_f32_e64 v68, -v64
	v_max_f32_e32 v66, 0, v65
	v_exp_f32_e64 v70, -v66
	v_mov_b32_e32 v67, v64
	v_pk_add_f32 v[116:117], v[116:117], v[66:67]
	v_mov_b32_e32 v71, v68
	v_pk_mul_f32 v[62:63], v[62:63], v[68:69] op_sel_hi:[1,0]
	v_pk_mul_f32 v[60:61], v[60:61], v[68:69] op_sel_hi:[1,0]
	v_pk_mul_f32 v[58:59], v[58:59], v[68:69] op_sel_hi:[1,0]
	v_pk_mul_f32 v[56:57], v[56:57], v[68:69] op_sel_hi:[1,0]
	v_pk_mul_f32 v[54:55], v[54:55], v[68:69] op_sel_hi:[1,0]
	v_pk_mul_f32 v[52:53], v[52:53], v[68:69] op_sel_hi:[1,0]
	v_pk_mul_f32 v[50:51], v[50:51], v[68:69] op_sel_hi:[1,0]
	v_pk_mul_f32 v[48:49], v[48:49], v[68:69] op_sel_hi:[1,0]
	v_pk_mul_f32 v[118:119], v[118:119], v[70:71]
	v_pk_mul_f32 v[46:47], v[46:47], v[70:71] op_sel_hi:[1,0]
	v_pk_mul_f32 v[44:45], v[44:45], v[70:71] op_sel_hi:[1,0]
	v_pk_mul_f32 v[42:43], v[42:43], v[70:71] op_sel_hi:[1,0]
	v_pk_mul_f32 v[40:41], v[40:41], v[70:71] op_sel_hi:[1,0]
	v_pk_mul_f32 v[38:39], v[38:39], v[70:71] op_sel_hi:[1,0]
	v_pk_mul_f32 v[36:37], v[36:37], v[70:71] op_sel_hi:[1,0]
	v_pk_mul_f32 v[34:35], v[34:35], v[70:71] op_sel_hi:[1,0]
	v_pk_mul_f32 v[32:33], v[32:33], v[70:71] op_sel_hi:[1,0]
	v_pk_add_f32 v[84:85], v[84:85], v[66:67] op_sel_hi:[1,0] neg_lo:[0,1] neg_hi:[0,1]
	v_pk_add_f32 v[86:87], v[86:87], v[66:67] op_sel_hi:[1,0] neg_lo:[0,1] neg_hi:[0,1]
	v_pk_add_f32 v[72:73], v[72:73], v[66:67] op_sel_hi:[1,0] neg_lo:[0,1] neg_hi:[0,1]
	v_pk_add_f32 v[74:75], v[74:75], v[66:67] op_sel_hi:[1,0] neg_lo:[0,1] neg_hi:[0,1]
	v_pk_add_f32 v[80:81], v[80:81], v[66:67] op_sel_hi:[1,0] neg_lo:[0,1] neg_hi:[0,1]
	v_pk_add_f32 v[82:83], v[82:83], v[66:67] op_sel_hi:[1,0] neg_lo:[0,1] neg_hi:[0,1]
	v_pk_add_f32 v[76:77], v[76:77], v[66:67] op_sel_hi:[1,0] neg_lo:[0,1] neg_hi:[0,1]
	v_pk_add_f32 v[78:79], v[78:79], v[66:67] op_sel_hi:[1,0] neg_lo:[0,1] neg_hi:[0,1]
	v_xor_b32_e32 v64, 0x80000000, v117
	v_pk_add_f32 v[68:69], v[116:117], 0 neg_lo:[1,1] neg_hi:[1,1]
.LBB0_308:
	ds_read_b128 v[204:207], v128 offset:5120
	ds_read_b128 v[208:211], v128 offset:5184
	ds_read_b128 v[216:219], v128 offset:7424
	ds_read_b128 v[220:223], v128 offset:7488
	ds_read_b128 v[224:227], v128 offset:9728
	ds_read_b128 v[228:231], v128 offset:9792
	ds_read_b128 v[232:235], v128 offset:12032
	ds_read_b128 v[236:239], v128 offset:12096
	v_exp_f32_e32 v131, v88
	v_exp_f32_e32 v130, v84
	v_exp_f32_e32 v133, v89
	v_exp_f32_e32 v132, v85
	v_exp_f32_e32 v135, v90
	v_exp_f32_e32 v134, v86
	v_exp_f32_e32 v147, v91
	v_exp_f32_e32 v146, v87
	v_exp_f32_e32 v149, v92
	v_exp_f32_e32 v148, v72
	v_exp_f32_e32 v150, v73
	v_pk_add_f32 v[72:73], v[130:131], 0 op_sel_hi:[1,0]
	v_exp_f32_e32 v151, v93
	v_pk_add_f32 v[72:73], v[132:133], v[72:73]
	v_exp_f32_e32 v153, v94
	v_pk_add_f32 v[72:73], v[134:135], v[72:73]
	v_exp_f32_e32 v152, v74
	v_exp_f32_e32 v155, v95
	v_pk_add_f32 v[72:73], v[146:147], v[72:73]
	v_exp_f32_e32 v154, v75
	v_exp_f32_e32 v157, v100
	v_pk_add_f32 v[72:73], v[148:149], v[72:73]
	v_exp_f32_e32 v156, v80
	v_exp_f32_e32 v159, v101
	v_pk_add_f32 v[72:73], v[150:151], v[72:73]
	v_exp_f32_e32 v158, v81
	v_exp_f32_e32 v161, v102
	v_exp_f32_e32 v160, v82
	v_pk_add_f32 v[72:73], v[152:153], v[72:73]
	v_exp_f32_e32 v103, v103
	v_exp_f32_e32 v102, v83
	v_pk_add_f32 v[72:73], v[154:155], v[72:73]
	v_exp_f32_e32 v163, v96
	v_exp_f32_e32 v162, v76
	v_pk_add_f32 v[72:73], v[156:157], v[72:73]
	v_exp_f32_e32 v97, v97
	v_exp_f32_e32 v96, v77
	v_pk_add_f32 v[72:73], v[158:159], v[72:73]
	v_exp_f32_e32 v165, v98
	v_exp_f32_e32 v164, v78
	v_pk_add_f32 v[72:73], v[160:161], v[72:73]
	v_exp_f32_e32 v99, v99
	v_exp_f32_e32 v98, v79
	v_pk_add_f32 v[72:73], v[102:103], v[72:73]
	v_mov_b32_e32 v69, v68
	v_pk_add_f32 v[72:73], v[162:163], v[72:73]
	v_mov_b32_e32 v65, v64
	v_pk_add_f32 v[72:73], v[96:97], v[72:73]
	v_mov_b32_e32 v66, v64
	v_pk_add_f32 v[72:73], v[164:165], v[72:73]
	v_mov_b32_e32 v67, v64
	v_pk_add_f32 v[72:73], v[98:99], v[72:73]
	v_cvt_pk_bf16_f32 v88, v131, v133
	v_cvt_pk_bf16_f32 v89, v135, v147
	v_cvt_pk_bf16_f32 v90, v149, v151
	v_cvt_pk_bf16_f32 v91, v153, v155
	v_cvt_pk_bf16_f32 v92, v157, v159
	v_cvt_pk_bf16_f32 v93, v161, v103
	v_cvt_pk_bf16_f32 v94, v163, v97
	v_cvt_pk_bf16_f32 v95, v165, v99
	v_pk_add_f32 v[100:101], v[72:73], v[118:119]
	v_cvt_pk_bf16_f32 v72, v130, v132
	v_cvt_pk_bf16_f32 v73, v134, v146
	v_cvt_pk_bf16_f32 v74, v148, v150
	v_cvt_pk_bf16_f32 v75, v152, v154
	v_cvt_pk_bf16_f32 v76, v156, v158
	v_cvt_pk_bf16_f32 v77, v160, v102
	v_cvt_pk_bf16_f32 v78, v162, v96
	v_cvt_pk_bf16_f32 v79, v164, v98
	v_mov_b32_e32 v70, v68
	v_mov_b32_e32 v71, v68
	s_setprio 1
	s_waitcnt lgkmcnt(0)
	v_mfma_f32_16x16x32_bf16 v[60:63], v[204:207], v[88:91], v[60:63]
	v_mfma_f32_16x16x32_bf16 v[80:83], v[204:207], v[72:75], v[44:47]
	v_mfma_f32_16x16x32_bf16 v[44:47], v[208:211], v[92:95], v[60:63]
	v_mfma_f32_16x16x32_bf16 v[60:63], v[208:211], v[76:79], v[80:83]
	v_mfma_f32_16x16x32_bf16 v[56:59], v[216:219], v[88:91], v[56:59]
	v_mfma_f32_16x16x32_bf16 v[40:43], v[216:219], v[72:75], v[40:43]
	v_mfma_f32_16x16x32_bf16 v[56:59], v[220:223], v[92:95], v[56:59]
	v_mfma_f32_16x16x32_bf16 v[40:43], v[220:223], v[76:79], v[40:43]
	v_mfma_f32_16x16x32_bf16 v[52:55], v[224:227], v[88:91], v[52:55]
	v_mfma_f32_16x16x32_bf16 v[36:39], v[224:227], v[72:75], v[36:39]
	v_mfma_f32_16x16x32_bf16 v[52:55], v[228:231], v[92:95], v[52:55]
	v_mfma_f32_16x16x32_bf16 v[36:39], v[228:231], v[76:79], v[36:39]
	v_mfma_f32_16x16x32_bf16 v[32:35], v[232:235], v[72:75], v[32:35]
	v_mfma_f32_16x16x32_bf16 v[48:51], v[232:235], v[88:91], v[48:51]
	v_mfma_f32_16x16x32_bf16 v[48:51], v[236:239], v[92:95], v[48:51]
	v_mfma_f32_16x16x32_bf16 v[32:35], v[236:239], v[76:79], v[32:35]
	s_setprio 0
	s_min_i32 s2, s4, s1
	s_waitcnt vmcnt(5)
	ds_write_b128 v122, v[8:11] offset:14336
	s_waitcnt vmcnt(4)
	ds_write_b64 v123, v[16:17] offset:19456
	ds_write_b64 v124, v[18:19] offset:19456
	s_waitcnt vmcnt(3)
	ds_write_b64 v125, v[12:13] offset:19456
	ds_write_b64 v126, v[14:15] offset:19456
	v_lshl_add_u32 v8, s2, 6, v108
	v_ashrrev_i32_e32 v9, 31, v8
	v_lshlrev_b64 v[8:9], 9, v[8:9]
	s_lshl_b32 s94, s2, 7
	v_lshl_add_u64 v[8:9], v[114:115], 0, v[8:9]
	v_lshl_add_u64 v[12:13], v[110:111], 0, s[94:95]
	v_lshl_add_u64 v[14:15], v[112:113], 0, s[94:95]
	s_waitcnt lgkmcnt(0)
	s_barrier
	global_load_dwordx4 v[8:11], v[8:9], off
	s_nop 0
	global_load_dwordx4 v[16:19], v[12:13], off
	s_nop 0
	global_load_dwordx4 v[12:15], v[14:15], off
	s_setprio 1
	ds_read_b128 v[72:75], v127 offset:14336
	ds_read_b128 v[76:79], v127 offset:15616
	ds_read_b128 v[248:251], v127 offset:16896
	ds_read_b128 v[130:133], v127 offset:18176
	s_waitcnt lgkmcnt(3)
	v_mfma_f32_16x16x32_bf16 v[88:91], v[72:75], v[0:3], v[64:67]
	v_mfma_f32_16x16x32_bf16 v[80:83], v[72:75], v[4:7], v[68:71]
	s_waitcnt lgkmcnt(2)
	v_mfma_f32_16x16x32_bf16 v[84:87], v[76:79], v[0:3], v[64:67]
	v_mfma_f32_16x16x32_bf16 v[76:79], v[76:79], v[4:7], v[68:71]
	s_waitcnt lgkmcnt(1)
	v_mfma_f32_16x16x32_bf16 v[96:99], v[248:251], v[0:3], v[64:67]
	v_mfma_f32_16x16x32_bf16 v[72:75], v[248:251], v[4:7], v[68:71]
	s_waitcnt lgkmcnt(0)
	v_mfma_f32_16x16x32_bf16 v[92:95], v[130:133], v[0:3], v[64:67]
	v_mfma_f32_16x16x32_bf16 v[64:67], v[130:133], v[4:7], v[68:71]
	s_setprio 0
	s_nop 1
	v_max_f32_e32 v68, v89, v89
	v_max_f32_e32 v69, v88, v88
	v_max_f32_e32 v68, v69, v68
	v_max_f32_e32 v69, v91, v91
	v_max_f32_e32 v70, v90, v90
	v_max_f32_e32 v69, v70, v69
	v_max_f32_e32 v70, v87, v87
	v_max_f32_e32 v71, v86, v86
	v_max_f32_e32 v70, v71, v70
	v_max3_f32 v70, v84, v85, v70
	v_max3_f32 v68, v68, v69, v70
	v_max_f32_e32 v69, v99, v99
	v_max_f32_e32 v70, v98, v98
	v_max_f32_e32 v69, v70, v69
	v_max_f32_e32 v70, v95, v95
	v_max_f32_e32 v71, v94, v94
	v_max_f32_e32 v70, v71, v70
	v_max3_f32 v69, v96, v97, v69
	v_max3_f32 v70, v92, v93, v70
	v_max3_f32 v68, v68, v69, v70
	v_mov_b32_e32 v69, v68
	v_max_f32_e32 v70, v80, v80
	v_max_f32_e32 v71, v82, v82
	v_max_f32_e32 v102, v78, v78
	s_mov_b32 s2, 0x41000000
	s_nop 1
	v_permlane16_swap_b32_e32 v69, v68
	v_max_f32_e32 v68, v68, v69
	v_mov_b32_e32 v69, v68
	s_nop 1
	v_permlane32_swap_b32_e32 v69, v68
	v_max_f32_e32 v68, v68, v69
	v_max_f32_e32 v69, v81, v81
	v_max_f32_e32 v69, v70, v69
	v_max_f32_e32 v70, v83, v83
	v_max_f32_e32 v70, v71, v70
	v_max_f32_e32 v71, v79, v79
	v_max_f32_e32 v71, v102, v71
	v_max3_f32 v71, v76, v77, v71
	v_max3_f32 v69, v69, v70, v71
	v_max_f32_e32 v70, v75, v75
	v_max_f32_e32 v71, v74, v74
	v_max_f32_e32 v70, v71, v70
	v_max_f32_e32 v71, v67, v67
	v_max_f32_e32 v102, v66, v66
	v_max_f32_e32 v71, v102, v71
	v_max3_f32 v70, v72, v73, v70
	v_max3_f32 v71, v64, v65, v71
	v_max3_f32 v69, v69, v70, v71
	v_mov_b32_e32 v70, v69
	s_nop 1
	v_permlane16_swap_b32_e32 v70, v69
	v_max_f32_e32 v69, v69, v70
	v_mov_b32_e32 v70, v69
	s_nop 1
	v_permlane32_swap_b32_e32 v70, v69
	v_max_f32_e32 v69, v69, v70
	v_max_f32_e32 v70, v68, v69
	v_cmp_lt_f32_e32 vcc, s2, v70
	s_cbranch_vccz .LBB0_305
	v_max_f32_e32 v68, v68, v68
	v_max_f32_e32 v68, 0, v68
	v_pk_add_f32 v[88:89], v[88:89], v[68:69] op_sel_hi:[1,0] neg_lo:[0,1] neg_hi:[0,1]
	v_pk_add_f32 v[90:91], v[90:91], v[68:69] op_sel_hi:[1,0] neg_lo:[0,1] neg_hi:[0,1]
	v_pk_add_f32 v[84:85], v[84:85], v[68:69] op_sel_hi:[1,0] neg_lo:[0,1] neg_hi:[0,1]
	v_pk_add_f32 v[86:87], v[86:87], v[68:69] op_sel_hi:[1,0] neg_lo:[0,1] neg_hi:[0,1]
	v_pk_add_f32 v[96:97], v[96:97], v[68:69] op_sel_hi:[1,0] neg_lo:[0,1] neg_hi:[0,1]
	v_pk_add_f32 v[98:99], v[98:99], v[68:69] op_sel_hi:[1,0] neg_lo:[0,1] neg_hi:[0,1]
	v_pk_add_f32 v[92:93], v[92:93], v[68:69] op_sel_hi:[1,0] neg_lo:[0,1] neg_hi:[0,1]
	v_pk_add_f32 v[94:95], v[94:95], v[68:69] op_sel_hi:[1,0] neg_lo:[0,1] neg_hi:[0,1]
	v_max_f32_e32 v69, v69, v69
	v_exp_f32_e64 v70, -v68
	v_max_f32_e32 v102, 0, v69
	v_exp_f32_e64 v118, -v102
	v_mov_b32_e32 v103, v68
	v_mov_b32_e32 v119, v70
	v_pk_mul_f32 v[46:47], v[46:47], v[70:71] op_sel_hi:[1,0]
	v_pk_mul_f32 v[44:45], v[44:45], v[70:71] op_sel_hi:[1,0]
	v_pk_mul_f32 v[58:59], v[58:59], v[70:71] op_sel_hi:[1,0]
	v_pk_mul_f32 v[56:57], v[56:57], v[70:71] op_sel_hi:[1,0]
	v_pk_mul_f32 v[54:55], v[54:55], v[70:71] op_sel_hi:[1,0]
	v_pk_mul_f32 v[52:53], v[52:53], v[70:71] op_sel_hi:[1,0]
	v_pk_mul_f32 v[50:51], v[50:51], v[70:71] op_sel_hi:[1,0]
	v_pk_mul_f32 v[48:49], v[48:49], v[70:71] op_sel_hi:[1,0]
	v_pk_add_f32 v[116:117], v[116:117], v[102:103]
	v_pk_mul_f32 v[100:101], v[100:101], v[118:119]
	v_pk_mul_f32 v[62:63], v[62:63], v[118:119] op_sel_hi:[1,0]
	v_pk_mul_f32 v[60:61], v[60:61], v[118:119] op_sel_hi:[1,0]
	v_pk_mul_f32 v[42:43], v[42:43], v[118:119] op_sel_hi:[1,0]
	v_pk_mul_f32 v[40:41], v[40:41], v[118:119] op_sel_hi:[1,0]
	v_pk_mul_f32 v[38:39], v[38:39], v[118:119] op_sel_hi:[1,0]
	v_pk_mul_f32 v[36:37], v[36:37], v[118:119] op_sel_hi:[1,0]
	v_pk_mul_f32 v[34:35], v[34:35], v[118:119] op_sel_hi:[1,0]
	v_pk_mul_f32 v[32:33], v[32:33], v[118:119] op_sel_hi:[1,0]
	v_pk_add_f32 v[80:81], v[80:81], v[102:103] op_sel_hi:[1,0] neg_lo:[0,1] neg_hi:[0,1]
	v_pk_add_f32 v[82:83], v[82:83], v[102:103] op_sel_hi:[1,0] neg_lo:[0,1] neg_hi:[0,1]
	v_pk_add_f32 v[76:77], v[76:77], v[102:103] op_sel_hi:[1,0] neg_lo:[0,1] neg_hi:[0,1]
	v_pk_add_f32 v[78:79], v[78:79], v[102:103] op_sel_hi:[1,0] neg_lo:[0,1] neg_hi:[0,1]
	v_pk_add_f32 v[72:73], v[72:73], v[102:103] op_sel_hi:[1,0] neg_lo:[0,1] neg_hi:[0,1]
	v_pk_add_f32 v[74:75], v[74:75], v[102:103] op_sel_hi:[1,0] neg_lo:[0,1] neg_hi:[0,1]
	v_pk_add_f32 v[64:65], v[64:65], v[102:103] op_sel_hi:[1,0] neg_lo:[0,1] neg_hi:[0,1]
	v_pk_add_f32 v[66:67], v[66:67], v[102:103] op_sel_hi:[1,0] neg_lo:[0,1] neg_hi:[0,1]
	s_branch .LBB0_305

	.amdhsa_kernel _Z4mega1Piii
		.amdhsa_group_segment_fixed_size 73744
		.amdhsa_private_segment_fixed_size 0
		.amdhsa_kernarg_size 936
		.amdhsa_user_sgpr_count 2
		.amdhsa_user_sgpr_dispatch_ptr 0
		.amdhsa_user_sgpr_queue_ptr 0
		.amdhsa_user_sgpr_kernarg_segment_ptr 1
		.amdhsa_user_sgpr_dispatch_id 0
		.amdhsa_user_sgpr_kernarg_preload_length 0
		.amdhsa_user_sgpr_kernarg_preload_offset 0
		.amdhsa_user_sgpr_private_segment_size 0
		.amdhsa_uses_dynamic_stack 0
		.amdhsa_enable_private_segment 0
		.amdhsa_system_sgpr_workgroup_id_x 1
		.amdhsa_system_sgpr_workgroup_id_y 0
		.amdhsa_system_sgpr_workgroup_id_z 0
		.amdhsa_system_sgpr_workgroup_info 0
		.amdhsa_system_vgpr_workitem_id 2
		.amdhsa_next_free_vgpr 256
		.amdhsa_next_free_sgpr 100
		.amdhsa_accum_offset 256
		.amdhsa_reserve_vcc 1
		.amdhsa_float_round_mode_32 0
		.amdhsa_float_round_mode_16_64 0
		.amdhsa_float_denorm_mode_32 3
		.amdhsa_float_denorm_mode_16_64 3
		.amdhsa_dx10_clamp 1
		.amdhsa_ieee_mode 1
		.amdhsa_fp16_overflow 0
		.amdhsa_tg_split 0
		.amdhsa_exception_fp_ieee_invalid_op 0
		.amdhsa_exception_fp_denorm_src 0
		.amdhsa_exception_fp_ieee_div_zero 0
		.amdhsa_exception_fp_ieee_overflow 0
		.amdhsa_exception_fp_ieee_underflow 0
		.amdhsa_exception_fp_ieee_inexact 0
		.amdhsa_exception_int_div_zero 0
	.end_amdhsa_kernel

amdhsa.kernels:
  - .agpr_count:     0
    .args:
      - .offset:         0
        .size:           664
        .value_kind:     by_value
      - .offset:         664
        .size:           4
        .value_kind:     by_value
      - .offset:         668
        .size:           4
        .value_kind:     by_value
      - .offset:         672
        .size:           4
        .value_kind:     by_value
      - .offset:         680
        .size:           4
        .value_kind:     hidden_block_count_x
      - .offset:         684
        .size:           4
        .value_kind:     hidden_block_count_y
      - .offset:         688
        .size:           4
        .value_kind:     hidden_block_count_z
      - .offset:         692
        .size:           2
        .value_kind:     hidden_group_size_x
      - .offset:         694
        .size:           2
        .value_kind:     hidden_group_size_y
      - .offset:         696
        .size:           2
        .value_kind:     hidden_group_size_z
      - .offset:         698
        .size:           2
        .value_kind:     hidden_remainder_x
      - .offset:         700
        .size:           2
        .value_kind:     hidden_remainder_y
      - .offset:         702
        .size:           2
        .value_kind:     hidden_remainder_z
      - .offset:         720
        .size:           8
        .value_kind:     hidden_global_offset_x
      - .offset:         728
        .size:           8
        .value_kind:     hidden_global_offset_y
      - .offset:         736
        .size:           8
        .value_kind:     hidden_global_offset_z
      - .offset:         744
        .size:           2
        .value_kind:     hidden_grid_dims
      - .offset:         768
        .size:           8
        .value_kind:     hidden_multigrid_sync_arg
    .group_segment_fixed_size: 73744
    .kernarg_segment_align: 8
    .kernarg_segment_size: 936
    .language:       OpenCL C
    .language_version:
      - 2
      - 0
    .max_flat_workgroup_size: 256
    .name:           _Z4mega1Piii
    .private_segment_fixed_size: 0
    .sgpr_count:     106
    .sgpr_spill_count: 355
    .symbol:         _Z4mega1Piii.kd
    .uniform_work_group_size: 1
    .uses_dynamic_stack: false
    .vgpr_count:     256
    .vgpr_spill_count: 0
    .wavefront_size: 64
